# W1 GEMM epilogue stores (the 302 MB/layer U tensor) issued with sc1 so they do not stay resident in the XCD L2
# baseline (speedup 1.0000x reference)
.LBB0_238:
	v_lshl_add_u32 v140, s42, 8, v144
	v_lshl_or_b32 v138, s79, 8, v146
	v_ashrrev_i32_e32 v141, 31, v140
	v_ashrrev_i32_e32 v139, 31, v138
	v_lshlrev_b64 v[142:143], 13, v[140:141]
	v_max_f32_e32 v124, v124, v124
	v_max_f32_e32 v125, v125, v125
	v_max_f32_e32 v126, v126, v126
	v_max_f32_e32 v127, v127, v127
	v_max_f32_e32 v116, v116, v116
	v_max_f32_e32 v117, v117, v117
	v_max_f32_e32 v118, v118, v118
	v_max_f32_e32 v119, v119, v119
	v_max_f32_e32 v112, v112, v112
	v_max_f32_e32 v113, v113, v113
	v_lshl_add_u64 v[164:165], s[2:3], 0, v[142:143]
	v_lshlrev_b64 v[142:143], 1, v[138:139]
	v_max_f32_e32 v124, 0, v124
	v_max_f32_e32 v125, 0, v125
	v_max_f32_e32 v126, 0, v126
	v_max_f32_e32 v127, 0, v127
	v_max_f32_e32 v120, v120, v120
	v_max_f32_e32 v121, v121, v121
	v_max_f32_e32 v122, v122, v122
	v_max_f32_e32 v123, v123, v123
	v_max_f32_e32 v116, 0, v116
	v_max_f32_e32 v117, 0, v117
	v_max_f32_e32 v118, 0, v118
	v_max_f32_e32 v119, 0, v119
	v_max_f32_e32 v112, 0, v112
	v_max_f32_e32 v113, 0, v113
	v_lshl_add_u64 v[138:139], v[164:165], 0, v[142:143]
	v_pk_mul_f32 v[126:127], v[126:127], v[126:127]
	v_pk_mul_f32 v[124:125], v[124:125], v[124:125]
	v_max_f32_e32 v120, 0, v120
	v_max_f32_e32 v121, 0, v121
	v_max_f32_e32 v122, 0, v122
	v_max_f32_e32 v123, 0, v123
	v_pk_mul_f32 v[118:119], v[118:119], v[118:119]
	v_pk_mul_f32 v[116:117], v[116:117], v[116:117]
	v_pk_mul_f32 v[112:113], v[112:113], v[112:113]
	v_cvt_pk_bf16_f32 v124, v124, v125
	v_cvt_pk_bf16_f32 v125, v126, v127
	v_pk_mul_f32 v[122:123], v[122:123], v[122:123]
	v_pk_mul_f32 v[120:121], v[120:121], v[120:121]
	v_max_f32_e32 v108, v108, v108
	v_cvt_pk_bf16_f32 v126, v120, v121
	v_cvt_pk_bf16_f32 v127, v122, v123
	global_store_dwordx4 v[138:139], v[124:127], off sc1
	v_cvt_pk_bf16_f32 v116, v116, v117
	v_cvt_pk_bf16_f32 v117, v118, v119
	v_cvt_pk_bf16_f32 v118, v112, v113
	v_or_b32_e32 v112, 16, v140
	v_ashrrev_i32_e32 v113, 31, v112
	v_lshlrev_b64 v[112:113], 13, v[112:113]
	v_max_f32_e32 v109, v109, v109
	v_max_f32_e32 v110, v110, v110
	v_max_f32_e32 v111, v111, v111
	v_max_f32_e32 v100, v100, v100
	v_max_f32_e32 v101, v101, v101
	v_max_f32_e32 v102, v102, v102
	v_max_f32_e32 v103, v103, v103
	v_max_f32_e32 v96, v96, v96
	v_max_f32_e32 v97, v97, v97
	v_max_f32_e32 v114, v114, v114
	v_max_f32_e32 v115, v115, v115
	v_lshl_add_u64 v[112:113], s[2:3], 0, v[112:113]
	v_max_f32_e32 v108, 0, v108
	v_max_f32_e32 v109, 0, v109
	v_max_f32_e32 v110, 0, v110
	v_max_f32_e32 v111, 0, v111
	v_max_f32_e32 v104, v104, v104
	v_max_f32_e32 v105, v105, v105
	v_max_f32_e32 v106, v106, v106
	v_max_f32_e32 v107, v107, v107
	v_max_f32_e32 v100, 0, v100
	v_max_f32_e32 v101, 0, v101
	v_max_f32_e32 v102, 0, v102
	v_max_f32_e32 v103, 0, v103
	v_max_f32_e32 v96, 0, v96
	v_max_f32_e32 v97, 0, v97
	v_max_f32_e32 v114, 0, v114
	v_max_f32_e32 v115, 0, v115
	v_lshl_add_u64 v[112:113], v[112:113], 0, v[142:143]
	v_pk_mul_f32 v[110:111], v[110:111], v[110:111]
	v_pk_mul_f32 v[108:109], v[108:109], v[108:109]
	v_max_f32_e32 v104, 0, v104
	v_max_f32_e32 v105, 0, v105
	v_max_f32_e32 v106, 0, v106
	v_max_f32_e32 v107, 0, v107
	v_pk_mul_f32 v[102:103], v[102:103], v[102:103]
	v_pk_mul_f32 v[100:101], v[100:101], v[100:101]
	v_pk_mul_f32 v[96:97], v[96:97], v[96:97]
	v_pk_mul_f32 v[114:115], v[114:115], v[114:115]
	v_pk_mul_f32 v[106:107], v[106:107], v[106:107]
	v_cvt_pk_bf16_f32 v119, v114, v115
	global_store_dwordx4 v[138:139], v[116:119], off offset:64 sc1
	v_cvt_pk_bf16_f32 v108, v108, v109
	v_cvt_pk_bf16_f32 v109, v110, v111
	v_pk_mul_f32 v[104:105], v[104:105], v[104:105]
	v_max_f32_e32 v92, v92, v92
	v_cvt_pk_bf16_f32 v110, v104, v105
	v_cvt_pk_bf16_f32 v111, v106, v107
	global_store_dwordx4 v[112:113], v[108:111], off sc1
	v_cvt_pk_bf16_f32 v100, v100, v101
	v_cvt_pk_bf16_f32 v101, v102, v103
	v_cvt_pk_bf16_f32 v102, v96, v97
	v_or_b32_e32 v96, 32, v140
	v_ashrrev_i32_e32 v97, 31, v96
	v_lshlrev_b64 v[96:97], 13, v[96:97]
	v_max_f32_e32 v93, v93, v93
	v_max_f32_e32 v94, v94, v94
	v_max_f32_e32 v95, v95, v95
	v_max_f32_e32 v84, v84, v84
	v_max_f32_e32 v85, v85, v85
	v_max_f32_e32 v86, v86, v86
	v_max_f32_e32 v87, v87, v87
	v_max_f32_e32 v80, v80, v80
	v_max_f32_e32 v81, v81, v81
	v_max_f32_e32 v98, v98, v98
	v_max_f32_e32 v99, v99, v99
	v_lshl_add_u64 v[96:97], s[2:3], 0, v[96:97]
	v_max_f32_e32 v92, 0, v92
	v_max_f32_e32 v93, 0, v93
	v_max_f32_e32 v94, 0, v94
	v_max_f32_e32 v95, 0, v95
	v_max_f32_e32 v88, v88, v88
	v_max_f32_e32 v89, v89, v89
	v_max_f32_e32 v90, v90, v90
	v_max_f32_e32 v91, v91, v91
	v_max_f32_e32 v84, 0, v84
	v_max_f32_e32 v85, 0, v85
	v_max_f32_e32 v86, 0, v86
	v_max_f32_e32 v87, 0, v87
	v_max_f32_e32 v80, 0, v80
	v_max_f32_e32 v81, 0, v81
	v_max_f32_e32 v98, 0, v98
	v_max_f32_e32 v99, 0, v99
	v_lshl_add_u64 v[96:97], v[96:97], 0, v[142:143]
	v_pk_mul_f32 v[94:95], v[94:95], v[94:95]
	v_pk_mul_f32 v[92:93], v[92:93], v[92:93]
	v_max_f32_e32 v88, 0, v88
	v_max_f32_e32 v89, 0, v89
	v_max_f32_e32 v90, 0, v90
	v_max_f32_e32 v91, 0, v91
	v_pk_mul_f32 v[86:87], v[86:87], v[86:87]
	v_pk_mul_f32 v[84:85], v[84:85], v[84:85]
	v_pk_mul_f32 v[80:81], v[80:81], v[80:81]
	v_pk_mul_f32 v[98:99], v[98:99], v[98:99]
	v_pk_mul_f32 v[90:91], v[90:91], v[90:91]
	v_cvt_pk_bf16_f32 v103, v98, v99
	global_store_dwordx4 v[112:113], v[100:103], off offset:64 sc1
	v_cvt_pk_bf16_f32 v92, v92, v93
	v_cvt_pk_bf16_f32 v93, v94, v95
	v_pk_mul_f32 v[88:89], v[88:89], v[88:89]
	v_max_f32_e32 v76, v76, v76
	v_cvt_pk_bf16_f32 v94, v88, v89
	v_cvt_pk_bf16_f32 v95, v90, v91
	global_store_dwordx4 v[96:97], v[92:95], off sc1
	v_cvt_pk_bf16_f32 v84, v84, v85
	v_cvt_pk_bf16_f32 v85, v86, v87
	v_cvt_pk_bf16_f32 v86, v80, v81
	v_or_b32_e32 v80, 48, v140
	v_ashrrev_i32_e32 v81, 31, v80
	v_lshlrev_b64 v[80:81], 13, v[80:81]
	v_max_f32_e32 v77, v77, v77
	v_max_f32_e32 v78, v78, v78
	v_max_f32_e32 v79, v79, v79
	v_max_f32_e32 v68, v68, v68
	v_max_f32_e32 v69, v69, v69
	v_max_f32_e32 v70, v70, v70
	v_max_f32_e32 v71, v71, v71
	v_max_f32_e32 v60, v60, v60
	v_max_f32_e32 v61, v61, v61
	v_max_f32_e32 v62, v62, v62
	v_max_f32_e32 v63, v63, v63
	v_max_f32_e32 v56, v56, v56
	v_max_f32_e32 v57, v57, v57
	v_max_f32_e32 v82, v82, v82
	v_max_f32_e32 v83, v83, v83
	v_lshl_add_u64 v[80:81], s[2:3], 0, v[80:81]
	v_max_f32_e32 v76, 0, v76
	v_max_f32_e32 v77, 0, v77
	v_max_f32_e32 v78, 0, v78
	v_max_f32_e32 v79, 0, v79
	v_max_f32_e32 v72, v72, v72
	v_max_f32_e32 v73, v73, v73
	v_max_f32_e32 v74, v74, v74
	v_max_f32_e32 v75, v75, v75
	v_max_f32_e32 v68, 0, v68
	v_max_f32_e32 v69, 0, v69
	v_max_f32_e32 v70, 0, v70
	v_max_f32_e32 v71, 0, v71
	v_max_f32_e32 v64, v64, v64
	v_max_f32_e32 v65, v65, v65
	v_max_f32_e32 v66, v66, v66
	v_max_f32_e32 v67, v67, v67
	v_max_f32_e32 v60, 0, v60
	v_max_f32_e32 v61, 0, v61
	v_max_f32_e32 v62, 0, v62
	v_max_f32_e32 v63, 0, v63
	v_max_f32_e32 v56, 0, v56
	v_max_f32_e32 v57, 0, v57
	v_max_f32_e32 v82, 0, v82
	v_max_f32_e32 v83, 0, v83
	v_lshl_add_u64 v[80:81], v[80:81], 0, v[142:143]
	v_pk_mul_f32 v[78:79], v[78:79], v[78:79]
	v_pk_mul_f32 v[76:77], v[76:77], v[76:77]
	v_max_f32_e32 v72, 0, v72
	v_max_f32_e32 v73, 0, v73
	v_max_f32_e32 v74, 0, v74
	v_max_f32_e32 v75, 0, v75
	v_pk_mul_f32 v[70:71], v[70:71], v[70:71]
	v_pk_mul_f32 v[68:69], v[68:69], v[68:69]
	v_max_f32_e32 v64, 0, v64
	v_max_f32_e32 v65, 0, v65
	v_max_f32_e32 v66, 0, v66
	v_max_f32_e32 v67, 0, v67
	v_pk_mul_f32 v[62:63], v[62:63], v[62:63]
	v_pk_mul_f32 v[60:61], v[60:61], v[60:61]
	v_pk_mul_f32 v[56:57], v[56:57], v[56:57]
	s_mov_b32 s11, 0x100000
	v_max_f32_e32 v52, v52, v52
	v_max_f32_e32 v53, v53, v53
	v_max_f32_e32 v54, v54, v54
	v_max_f32_e32 v55, v55, v55
	v_max_f32_e32 v44, v44, v44
	v_max_f32_e32 v45, v45, v45
	v_max_f32_e32 v46, v46, v46
	v_max_f32_e32 v47, v47, v47
	v_pk_mul_f32 v[82:83], v[82:83], v[82:83]
	v_pk_mul_f32 v[74:75], v[74:75], v[74:75]
	v_cvt_pk_bf16_f32 v87, v82, v83
	global_store_dwordx4 v[96:97], v[84:87], off offset:64 sc1
	v_cvt_pk_bf16_f32 v76, v76, v77
	v_cvt_pk_bf16_f32 v77, v78, v79
	v_pk_mul_f32 v[72:73], v[72:73], v[72:73]
	v_pk_mul_f32 v[66:67], v[66:67], v[66:67]
	v_cvt_pk_bf16_f32 v78, v72, v73
	v_cvt_pk_bf16_f32 v79, v74, v75
	global_store_dwordx4 v[80:81], v[76:79], off sc1
	v_cvt_pk_bf16_f32 v68, v68, v69
	v_cvt_pk_bf16_f32 v69, v70, v71
	v_pk_mul_f32 v[64:65], v[64:65], v[64:65]
	v_max_f32_e32 v58, v58, v58
	v_cvt_pk_bf16_f32 v70, v64, v65
	v_cvt_pk_bf16_f32 v71, v66, v67
	global_store_dwordx4 v[80:81], v[68:71], off offset:64 sc1
	v_cvt_pk_bf16_f32 v60, v60, v61
	v_cvt_pk_bf16_f32 v61, v62, v63
	v_max_f32_e32 v59, v59, v59
	v_cvt_pk_bf16_f32 v62, v56, v57
	v_add_co_u32_e32 v56, vcc, s11, v138
	v_max_f32_e32 v52, 0, v52
	v_max_f32_e32 v53, 0, v53
	v_max_f32_e32 v54, 0, v54
	v_max_f32_e32 v55, 0, v55
	v_max_f32_e32 v44, 0, v44
	v_max_f32_e32 v45, 0, v45
	v_max_f32_e32 v46, 0, v46
	v_max_f32_e32 v47, 0, v47
	v_max_f32_e32 v58, 0, v58
	v_max_f32_e32 v59, 0, v59
	v_addc_co_u32_e32 v57, vcc, 0, v139, vcc
	v_pk_mul_f32 v[54:55], v[54:55], v[54:55]
	v_pk_mul_f32 v[52:53], v[52:53], v[52:53]
	v_pk_mul_f32 v[46:47], v[46:47], v[46:47]
	v_pk_mul_f32 v[44:45], v[44:45], v[44:45]
	v_pk_mul_f32 v[58:59], v[58:59], v[58:59]
	v_max_f32_e32 v40, v40, v40
	v_cvt_pk_bf16_f32 v63, v58, v59
	global_store_dwordx4 v[56:57], v[60:63], off sc1
	v_cvt_pk_bf16_f32 v52, v52, v53
	v_cvt_pk_bf16_f32 v53, v54, v55
	v_cvt_pk_bf16_f32 v54, v44, v45
	v_cvt_pk_bf16_f32 v55, v46, v47
	v_max_f32_e32 v44, v48, v48
	v_max_f32_e32 v45, v49, v49
	v_max_f32_e32 v46, v50, v50
	v_max_f32_e32 v47, v51, v51
	v_max_f32_e32 v41, v41, v41
	s_mov_b64 s[16:17], 0x100000
	v_max_f32_e32 v44, 0, v44
	v_max_f32_e32 v45, 0, v45
	v_max_f32_e32 v46, 0, v46
	v_max_f32_e32 v47, 0, v47
	v_max_f32_e32 v40, 0, v40
	v_max_f32_e32 v41, 0, v41
	v_lshl_add_u64 v[64:65], v[138:139], 0, s[16:17]
	v_pk_mul_f32 v[46:47], v[46:47], v[46:47]
	v_pk_mul_f32 v[44:45], v[44:45], v[44:45]
	v_pk_mul_f32 v[40:41], v[40:41], v[40:41]
	s_mov_b32 s11, 0x120000
	v_max_f32_e32 v36, v36, v36
	v_max_f32_e32 v37, v37, v37
	v_max_f32_e32 v38, v38, v38
	v_max_f32_e32 v39, v39, v39
	v_max_f32_e32 v28, v28, v28
	v_max_f32_e32 v29, v29, v29
	v_max_f32_e32 v30, v30, v30
	v_max_f32_e32 v31, v31, v31
	global_store_dwordx4 v[64:65], v[52:55], off offset:64 sc1
	v_cvt_pk_bf16_f32 v44, v44, v45
	v_cvt_pk_bf16_f32 v45, v46, v47
	v_max_f32_e32 v42, v42, v42
	v_max_f32_e32 v43, v43, v43
	v_cvt_pk_bf16_f32 v46, v40, v41
	v_add_co_u32_e32 v40, vcc, s11, v138
	v_max_f32_e32 v36, 0, v36
	v_max_f32_e32 v37, 0, v37
	v_max_f32_e32 v38, 0, v38
	v_max_f32_e32 v39, 0, v39
	v_max_f32_e32 v28, 0, v28
	v_max_f32_e32 v29, 0, v29
	v_max_f32_e32 v30, 0, v30
	v_max_f32_e32 v31, 0, v31
	v_max_f32_e32 v42, 0, v42
	v_max_f32_e32 v43, 0, v43
	v_addc_co_u32_e32 v41, vcc, 0, v139, vcc
	v_pk_mul_f32 v[38:39], v[38:39], v[38:39]
	v_pk_mul_f32 v[36:37], v[36:37], v[36:37]
	v_pk_mul_f32 v[30:31], v[30:31], v[30:31]
	v_pk_mul_f32 v[28:29], v[28:29], v[28:29]
	v_pk_mul_f32 v[42:43], v[42:43], v[42:43]
	v_max_f32_e32 v24, v24, v24
	v_cvt_pk_bf16_f32 v47, v42, v43
	global_store_dwordx4 v[40:41], v[44:47], off sc1
	v_cvt_pk_bf16_f32 v36, v36, v37
	v_cvt_pk_bf16_f32 v37, v38, v39
	v_cvt_pk_bf16_f32 v38, v28, v29
	v_cvt_pk_bf16_f32 v39, v30, v31
	v_max_f32_e32 v28, v32, v32
	v_max_f32_e32 v29, v33, v33
	v_max_f32_e32 v30, v34, v34
	v_max_f32_e32 v31, v35, v35
	v_max_f32_e32 v25, v25, v25
	s_mov_b64 s[16:17], 0x120000
	v_max_f32_e32 v28, 0, v28
	v_max_f32_e32 v29, 0, v29
	v_max_f32_e32 v30, 0, v30
	v_max_f32_e32 v31, 0, v31
	v_max_f32_e32 v24, 0, v24
	v_max_f32_e32 v25, 0, v25
	v_lshl_add_u64 v[52:53], v[138:139], 0, s[16:17]
	v_pk_mul_f32 v[30:31], v[30:31], v[30:31]
	v_pk_mul_f32 v[28:29], v[28:29], v[28:29]
	v_pk_mul_f32 v[24:25], v[24:25], v[24:25]
	s_mov_b32 s11, 0x140000
	v_max_f32_e32 v20, v20, v20
	v_max_f32_e32 v21, v21, v21
	v_max_f32_e32 v22, v22, v22
	v_max_f32_e32 v23, v23, v23
	v_max_f32_e32 v12, v12, v12
	v_max_f32_e32 v13, v13, v13
	v_max_f32_e32 v14, v14, v14
	v_max_f32_e32 v15, v15, v15
	global_store_dwordx4 v[52:53], v[36:39], off offset:64 sc1
	v_cvt_pk_bf16_f32 v28, v28, v29
	v_cvt_pk_bf16_f32 v29, v30, v31
	v_max_f32_e32 v26, v26, v26
	v_max_f32_e32 v27, v27, v27
	v_cvt_pk_bf16_f32 v30, v24, v25
	v_add_co_u32_e32 v24, vcc, s11, v138
	v_max_f32_e32 v20, 0, v20
	v_max_f32_e32 v21, 0, v21
	v_max_f32_e32 v22, 0, v22
	v_max_f32_e32 v23, 0, v23
	v_max_f32_e32 v12, 0, v12
	v_max_f32_e32 v13, 0, v13
	v_max_f32_e32 v14, 0, v14
	v_max_f32_e32 v15, 0, v15
	v_max_f32_e32 v26, 0, v26
	v_max_f32_e32 v27, 0, v27
	v_addc_co_u32_e32 v25, vcc, 0, v139, vcc
	v_pk_mul_f32 v[22:23], v[22:23], v[22:23]
	v_pk_mul_f32 v[20:21], v[20:21], v[20:21]
	v_pk_mul_f32 v[14:15], v[14:15], v[14:15]
	v_pk_mul_f32 v[12:13], v[12:13], v[12:13]
	v_pk_mul_f32 v[26:27], v[26:27], v[26:27]
	v_max_f32_e32 v8, v8, v8
	v_cvt_pk_bf16_f32 v31, v26, v27
	global_store_dwordx4 v[24:25], v[28:31], off sc1
	v_cvt_pk_bf16_f32 v20, v20, v21
	v_cvt_pk_bf16_f32 v21, v22, v23
	v_cvt_pk_bf16_f32 v22, v12, v13
	v_cvt_pk_bf16_f32 v23, v14, v15
	v_max_f32_e32 v12, v16, v16
	v_max_f32_e32 v13, v17, v17
	v_max_f32_e32 v14, v18, v18
	v_max_f32_e32 v15, v19, v19
	v_max_f32_e32 v9, v9, v9
	s_mov_b64 s[16:17], 0x140000
	v_max_f32_e32 v12, 0, v12
	v_max_f32_e32 v13, 0, v13
	v_max_f32_e32 v14, 0, v14
	v_max_f32_e32 v15, 0, v15
	v_max_f32_e32 v8, 0, v8
	v_max_f32_e32 v9, 0, v9
	v_lshl_add_u64 v[36:37], v[138:139], 0, s[16:17]
	v_pk_mul_f32 v[14:15], v[14:15], v[14:15]
	v_pk_mul_f32 v[12:13], v[12:13], v[12:13]
	v_pk_mul_f32 v[8:9], v[8:9], v[8:9]
	s_mov_b32 s11, 0x160000
	global_store_dwordx4 v[36:37], v[20:23], off offset:64 sc1
	v_cvt_pk_bf16_f32 v12, v12, v13
	v_cvt_pk_bf16_f32 v13, v14, v15
	v_cvt_pk_bf16_f32 v14, v8, v9
	v_add_co_u32_e32 v8, vcc, s11, v138
	v_max_f32_e32 v4, v4, v4
	v_max_f32_e32 v5, v5, v5
	v_max_f32_e32 v6, v6, v6
	v_max_f32_e32 v7, v7, v7
	s_mov_b64 s[16:17], 0x160000
	v_max_f32_e32 v10, v10, v10
	v_max_f32_e32 v11, v11, v11
	v_addc_co_u32_e32 v9, vcc, 0, v139, vcc
	v_max_f32_e32 v4, 0, v4
	v_max_f32_e32 v5, 0, v5
	v_max_f32_e32 v6, 0, v6
	v_max_f32_e32 v7, 0, v7
	v_max_f32_e32 v0, v0, v0
	v_max_f32_e32 v1, v1, v1
	v_max_f32_e32 v2, v2, v2
	v_max_f32_e32 v3, v3, v3
	v_lshl_add_u64 v[20:21], v[138:139], 0, s[16:17]
	v_max_f32_e32 v10, 0, v10
	v_max_f32_e32 v11, 0, v11
	v_pk_mul_f32 v[6:7], v[6:7], v[6:7]
	v_pk_mul_f32 v[4:5], v[4:5], v[4:5]
	v_max_f32_e32 v0, 0, v0
	v_max_f32_e32 v1, 0, v1
	v_max_f32_e32 v2, 0, v2
	v_max_f32_e32 v3, 0, v3
	s_andn2_b64 vcc, exec, s[38:39]
	s_mov_b64 s[16:17], -1
	s_mov_b64 s[80:81], 0xc00000
	s_mov_b64 s[84:85], 0xc00800
	v_pk_mul_f32 v[10:11], v[10:11], v[10:11]
	v_pk_mul_f32 v[2:3], v[2:3], v[2:3]
	v_cvt_pk_bf16_f32 v15, v10, v11
	global_store_dwordx4 v[8:9], v[12:15], off sc1
	v_cvt_pk_bf16_f32 v4, v4, v5
	v_cvt_pk_bf16_f32 v5, v6, v7
	v_pk_mul_f32 v[0:1], v[0:1], v[0:1]
	s_nop 0
	v_cvt_pk_bf16_f32 v6, v0, v1
	v_cvt_pk_bf16_f32 v7, v2, v3
	global_store_dwordx4 v[20:21], v[4:7], off offset:64 sc1
	s_cbranch_vccnz .LBB0_231
	s_andn2_b64 vcc, exec, s[0:1]
	s_cbranch_vccnz .LBB0_230
	s_barrier
	s_branch .LBB0_230
